# grid-barrier census (first xcd barrier): 16 counter loads issued together instead of 12 serialized round trips
# baseline (speedup 1.0000x reference)
.LBB0_235:
	v_mov_b64_e32 v[12:13], s[36:37]
	global_load_dword v1, v[12:13], off offset:1024 sc1
	s_waitcnt lgkmcnt(0)
	global_load_dword v0, v[12:13], off offset:1280 sc1
	global_load_dword v2, v[12:13], off offset:1536 sc1
	s_or_b64 s[16:17], s[16:17], exec
	s_or_b64 s[14:15], s[14:15], exec
	global_load_dword v3, v[12:13], off offset:1792 sc1
	global_load_dword v4, v[12:13], off offset:2048 sc1
	global_load_dword v5, v[12:13], off offset:2304 sc1
	global_load_dword v6, v[12:13], off offset:2560 sc1
	global_load_dword v7, v[12:13], off offset:2816 sc1
	global_load_dword v8, v[12:13], off offset:3072 sc1
	global_load_dword v9, v[12:13], off offset:3328 sc1
	global_load_dword v10, v[12:13], off offset:3584 sc1
	global_load_dword v11, v[12:13], off offset:3840 sc1
	v_mov_b64_e32 v[12:13], s[2:3]
	global_load_dword v12, v[12:13], off sc1
	v_mov_b64_e32 v[14:15], s[4:5]
	global_load_dword v13, v[14:15], off sc1
	v_mov_b64_e32 v[14:15], s[6:7]
	global_load_dword v14, v[14:15], off sc1
	v_mov_b64_e32 v[16:17], s[8:9]
	global_load_dword v15, v[16:17], off sc1
	s_waitcnt vmcnt(0) lgkmcnt(0)
	v_add_u32_e32 v18, v0, v1
	v_add_u32_e32 v18, v18, v2
	v_add_u32_e32 v18, v18, v3
	v_add_u32_e32 v18, v18, v4
	v_add_u32_e32 v18, v18, v5
	v_add_u32_e32 v18, v18, v6
	v_add_u32_e32 v18, v18, v7
	v_add_u32_e32 v18, v18, v8
	v_add_u32_e32 v18, v18, v9
	v_add_u32_e32 v18, v18, v10
	v_add_u32_e32 v18, v18, v11
	v_add_u32_e32 v18, v18, v12
	v_add_u32_e32 v18, v18, v13
	v_add_u32_e32 v18, v18, v14
	v_add_u32_e32 v18, v18, v15
	v_mov_b32_e32 v16, v18
	v_cmp_ne_u32_e32 vcc, s74, v16
	s_and_saveexec_b64 s[18:19], vcc
	s_cbranch_execz .LBB0_234
	s_and_b32 s22, s28, 0xff
	s_mov_b64 s[20:21], -1
	s_cmp_eq_u32 s22, 0
	s_mov_b64 s[24:25], -1
	s_mov_b64 s[22:23], -1
	s_sleep 1
	s_cbranch_scc1 .LBB0_238
	s_and_saveexec_b64 s[26:27], s[24:25]
	s_cbranch_execz .LBB0_233
	s_branch .LBB0_241
